# P8 residual epilogue rewritten with 16-byte loads/stores (weight rows stored permuted in the prologue so each lane owns 8 contiguous columns)
# speedup vs baseline: 1.0127x; 1.0046x over previous
.LBB0_17:
	s_load_dwordx16 s[4:19], s[0:1], 0x40
	s_cmp_lt_i32 s86, 1
	v_lshrrev_b32_e32 v159, 6, v158
	s_waitcnt lgkmcnt(0)
	v_writelane_b32 v252, s4, 7
	s_nop 1
	v_writelane_b32 v252, s5, 8
	v_writelane_b32 v252, s6, 9
	v_writelane_b32 v252, s7, 10
	v_writelane_b32 v252, s8, 11
	v_writelane_b32 v252, s9, 12
	v_writelane_b32 v252, s10, 13
	v_writelane_b32 v252, s11, 14
	v_writelane_b32 v252, s12, 15
	v_writelane_b32 v252, s13, 16
	v_writelane_b32 v252, s14, 17
	v_writelane_b32 v252, s15, 18
	v_writelane_b32 v252, s16, 19
	v_writelane_b32 v252, s17, 20
	v_writelane_b32 v252, s18, 21
	v_writelane_b32 v252, s19, 22
	s_load_dwordx16 s[4:19], s[0:1], 0x80
	s_cselect_b64 s[0:1], -1, 0
	s_cmp_gt_i32 s87, 0
	s_cselect_b64 s[2:3], -1, 0
	s_and_b64 s[0:1], s[0:1], s[2:3]
	s_waitcnt lgkmcnt(0)
	v_writelane_b32 v252, s4, 23
	s_andn2_b64 vcc, exec, s[0:1]
	s_nop 0
	v_writelane_b32 v252, s5, 24
	v_writelane_b32 v252, s6, 25
	v_writelane_b32 v252, s7, 26
	v_writelane_b32 v252, s8, 27
	v_writelane_b32 v252, s9, 28
	v_writelane_b32 v252, s10, 29
	v_writelane_b32 v252, s11, 30
	v_writelane_b32 v252, s12, 31
	v_writelane_b32 v252, s13, 32
	v_writelane_b32 v252, s14, 33
	v_writelane_b32 v252, s15, 34
	v_writelane_b32 v252, s16, 35
	v_writelane_b32 v252, s17, 36
	v_writelane_b32 v252, s18, 37
	v_writelane_b32 v252, s19, 38
	s_cbranch_vccnz .LBB0_264
	v_lshrrev_b32_e32 v0, 6, v158
	v_lshl_add_u32 v64, s33, 3, v0
	s_movk_i32 s0, 0x23ff
	v_cmp_lt_i32_e32 vcc, s0, v64
	s_and_saveexec_b64 s[0:1], vcc
	s_xor_b64 s[0:1], exec, s[0:1]
	s_lshl_b32 s2, s33, 9
	s_or_saveexec_b64 s[4:5], s[0:1]
	v_and_b32_e32 v93, 63, v158
	s_lshl_b32 s12, s88, 3
	v_mov_b32_e32 v1, s2
	s_xor_b64 exec, exec, s[4:5]
	s_cbranch_execz .LBB0_186
	s_movk_i32 s0, 0x4100
	v_mad_u32_u24 v1, v0, s0, 0
	v_lshrrev_b32_e32 v66, 4, v93
	s_movk_i32 s0, 0x104
	v_mov_b32_e32 v3, 0x410
	v_mad_u32_u24 v102, v66, s0, v3
	v_mov_b32_e32 v3, 0x820
	v_mad_u32_u24 v103, v66, s0, v3
	v_mov_b32_e32 v3, 0xc30
	v_mad_u32_u24 v104, v66, s0, v3
	v_mov_b32_e32 v3, 0x1040
	v_mad_u32_u24 v105, v66, s0, v3
	v_mov_b32_e32 v3, 0x1450
	v_mad_u32_u24 v106, v66, s0, v3
	v_mov_b32_e32 v3, 0x1860
	v_mad_u32_u24 v107, v66, s0, v3
	v_mov_b32_e32 v3, 0x1c70
	v_mad_u32_u24 v108, v66, s0, v3
	v_mov_b32_e32 v3, 0x2080
	v_mad_u32_u24 v109, v66, s0, v3
	v_mov_b32_e32 v3, 0x2490
	v_mad_u32_u24 v110, v66, s0, v3
	v_mov_b32_e32 v3, 0x28a0
	v_mad_u32_u24 v111, v66, s0, v3
	v_mov_b32_e32 v3, 0x2cb0
	v_lshlrev_b32_e32 v2, 4, v158
	v_mad_u32_u24 v112, v66, s0, v3
	v_lshlrev_b32_e32 v3, 3, v158
	v_and_b32_e32 v2, 0xf0, v2
	v_and_b32_e32 v3, 56, v3
	v_add_u32_e32 v65, v1, v2
	v_lshlrev_b32_e32 v4, 1, v3
	v_mov_b32_e32 v5, 0
	v_readlane_b32 s64, v252, 7
	v_mad_u32_u24 v95, v66, s0, v65
	v_lshl_add_u64 v[68:69], s[84:85], 0, v[4:5]
	s_mov_b64 s[0:1], 0x5c00000
	v_readlane_b32 s78, v252, 21
	v_readlane_b32 s79, v252, 22
	v_readlane_b32 s16, v252, 23
	s_cmp_lg_u64 s[54:55], 0
	v_lshl_add_u64 v[70:71], v[68:69], 0, s[0:1]
	s_mov_b64 s[0:1], 0x800000
	v_readlane_b32 s17, v252, 24
	s_cselect_b64 s[6:7], -1, 0
	s_cmp_lg_u64 s[78:79], 0
	v_lshrrev_b32_e32 v113, 3, v93
	v_and_b32_e32 v254, 3, v113
	v_and_b32_e32 v255, 4, v113
	v_lshl_or_b32 v254, v255, 2, v254
	v_lshl_add_u64 v[72:73], v[68:69], 0, s[0:1]
	s_mov_b64 s[0:1], 0xa00000
	v_readlane_b32 s28, v252, 35
	v_readlane_b32 s29, v252, 36
	s_cselect_b64 s[8:9], -1, 0
	s_cmp_lg_u64 s[16:17], 0
	v_mul_u32_u24_e32 v6, 0x104, v3
	v_lshlrev_b32_e32 v3, 2, v113
	v_lshl_add_u64 v[74:75], v[68:69], 0, s[0:1]
	s_mov_b64 s[0:1], 0xe00000
	s_cselect_b64 s[10:11], -1, 0
	s_cmp_lg_u64 s[28:29], 0
	v_add3_u32 v114, v1, v6, v3
	v_lshl_add_u64 v[76:77], v[68:69], 0, s[0:1]
	s_mov_b64 s[0:1], 0x1000000
	v_mov_b32_e32 v3, v5
	v_readlane_b32 s76, v252, 19
	v_readlane_b32 s77, v252, 20
	v_readlane_b32 s18, v252, 25
	v_readlane_b32 s19, v252, 26
	v_readlane_b32 s20, v252, 27
	v_readlane_b32 s21, v252, 28
	v_readlane_b32 s24, v252, 31
	v_readlane_b32 s25, v252, 32
	v_readlane_b32 s26, v252, 33
	v_readlane_b32 s27, v252, 34
	v_readlane_b32 s30, v252, 37
	v_readlane_b32 s31, v252, 38
	s_cselect_b64 s[14:15], -1, 0
	s_lshl_b32 s13, s33, 9
	v_or_b32_e32 v115, 8, v113
	v_or_b32_e32 v116, 16, v113
	v_or_b32_e32 v117, 24, v113
	v_or_b32_e32 v118, 32, v113
	v_or_b32_e32 v119, 40, v113
	v_or_b32_e32 v120, 48, v113
	v_or_b32_e32 v121, 56, v113
	v_lshl_add_u64 v[78:79], v[68:69], 0, s[0:1]
	v_lshl_add_u64 v[80:81], s[56:57], 0, v[2:3]
	v_lshl_add_u64 v[82:83], s[76:77], 0, v[2:3]
	v_lshl_add_u64 v[84:85], s[18:19], 0, v[2:3]
	v_lshl_add_u64 v[86:87], s[20:21], 0, v[2:3]
	v_lshl_add_u64 v[88:89], s[26:27], 0, v[2:3]
	v_lshl_add_u64 v[90:91], s[30:31], 0, v[2:3]
	v_mov_b32_e32 v67, v5
	v_lshl_add_u32 v92, v0, 6, s13
	s_lshl_b32 s24, s12, 6
	s_movk_i32 s25, 0xbff
	s_mov_b32 s26, 0x2aaaaaab
	s_movk_i32 s27, 0xffa0
	s_movk_i32 s28, 0xe800
	s_movk_i32 s29, 0x6040
	s_movk_i32 s30, 0x3ff
	s_movk_i32 s31, 0xff
	v_mov_b32_e32 v122, 0x400
	v_mov_b32_e32 v94, v64
	s_movk_i32 s34, 0x1ff
	s_movk_i32 s35, 0x23ff
	s_mov_b64 s[16:17], 0
	v_readlane_b32 s65, v252, 8
	v_readlane_b32 s66, v252, 9
	v_readlane_b32 s67, v252, 10
	v_readlane_b32 s68, v252, 11
	v_readlane_b32 s69, v252, 12
	v_readlane_b32 s70, v252, 13
	v_readlane_b32 s71, v252, 14
	v_readlane_b32 s72, v252, 15
	v_readlane_b32 s73, v252, 16
	v_readlane_b32 s74, v252, 17
	v_readlane_b32 s75, v252, 18
	v_readlane_b32 s22, v252, 29
	v_readlane_b32 s23, v252, 30
	s_branch .LBB0_25

.LBB0_137:
	v_ashrrev_i32_e32 v0, 31, v123
	v_lshrrev_b32_e32 v0, 27, v0
	v_add_u32_e32 v1, v123, v0
	v_and_b32_e32 v0, 0x3ffffe0, v1
	v_lshlrev_b32_e32 v1, 1, v1
	v_and_b32_e32 v62, 0xffffffc0, v1
	v_sub_u32_e32 v0, v123, v0
	v_or_b32_e32 v96, v62, v66
	v_lshlrev_b32_e32 v0, 6, v0
	v_or_b32_e32 v4, 4, v96
	v_ashrrev_i32_e32 v1, 31, v0
	v_ashrrev_i32_e32 v97, 31, v96
	v_ashrrev_i32_e32 v5, 31, v4
	v_lshl_add_u64 v[98:99], v[0:1], 2, v[88:89]
	v_lshlrev_b64 v[2:3], 13, v[96:97]
	v_lshlrev_b64 v[4:5], 13, v[4:5]
	v_lshl_add_u64 v[2:3], v[98:99], 0, v[2:3]
	v_lshl_add_u64 v[6:7], v[98:99], 0, v[4:5]
	v_or_b32_e32 v10, 8, v96
	v_or_b32_e32 v12, 12, v96
	global_load_dwordx4 v[2:5], v[2:3], off nt
	s_nop 0
	global_load_dwordx4 v[6:9], v[6:7], off nt
	v_ashrrev_i32_e32 v11, 31, v10
	v_ashrrev_i32_e32 v13, 31, v12
	v_lshlrev_b64 v[10:11], 13, v[10:11]
	v_lshlrev_b64 v[12:13], 13, v[12:13]
	v_lshl_add_u64 v[10:11], v[98:99], 0, v[10:11]
	v_lshl_add_u64 v[14:15], v[98:99], 0, v[12:13]
	global_load_dwordx4 v[10:13], v[10:11], off nt
	s_nop 0
	global_load_dwordx4 v[14:17], v[14:15], off nt
	v_or_b32_e32 v18, 16, v96
	v_or_b32_e32 v20, 20, v96
	v_ashrrev_i32_e32 v19, 31, v18
	v_ashrrev_i32_e32 v21, 31, v20
	v_lshlrev_b64 v[18:19], 13, v[18:19]
	v_lshlrev_b64 v[20:21], 13, v[20:21]
	v_lshl_add_u64 v[18:19], v[98:99], 0, v[18:19]
	v_lshl_add_u64 v[22:23], v[98:99], 0, v[20:21]
	global_load_dwordx4 v[18:21], v[18:19], off nt
	s_nop 0
	global_load_dwordx4 v[22:25], v[22:23], off nt
	v_or_b32_e32 v26, 24, v96
	v_or_b32_e32 v28, 28, v96
	v_ashrrev_i32_e32 v27, 31, v26
	v_ashrrev_i32_e32 v29, 31, v28
	v_lshlrev_b64 v[26:27], 13, v[26:27]
	v_lshlrev_b64 v[28:29], 13, v[28:29]
	v_lshl_add_u64 v[26:27], v[98:99], 0, v[26:27]
	v_lshl_add_u64 v[30:31], v[98:99], 0, v[28:29]
	global_load_dwordx4 v[26:29], v[26:27], off nt
	s_nop 0
	global_load_dwordx4 v[30:33], v[30:31], off nt
	v_or_b32_e32 v34, 32, v96
	v_or_b32_e32 v36, 36, v96
	v_ashrrev_i32_e32 v35, 31, v34
	v_ashrrev_i32_e32 v37, 31, v36
	v_lshlrev_b64 v[34:35], 13, v[34:35]
	v_lshlrev_b64 v[36:37], 13, v[36:37]
	v_lshl_add_u64 v[34:35], v[98:99], 0, v[34:35]
	v_lshl_add_u64 v[38:39], v[98:99], 0, v[36:37]
	global_load_dwordx4 v[34:37], v[34:35], off nt
	s_nop 0
	global_load_dwordx4 v[38:41], v[38:39], off nt
	v_or_b32_e32 v42, 40, v96
	v_or_b32_e32 v44, 44, v96
	v_ashrrev_i32_e32 v43, 31, v42
	v_ashrrev_i32_e32 v45, 31, v44
	v_lshlrev_b64 v[42:43], 13, v[42:43]
	v_lshlrev_b64 v[44:45], 13, v[44:45]
	v_lshl_add_u64 v[42:43], v[98:99], 0, v[42:43]
	v_lshl_add_u64 v[46:47], v[98:99], 0, v[44:45]
	v_or_b32_e32 v50, 48, v96
	global_load_dwordx4 v[42:45], v[42:43], off nt
	s_nop 0
	global_load_dwordx4 v[46:49], v[46:47], off nt
	v_ashrrev_i32_e32 v51, 31, v50
	v_lshlrev_b64 v[50:51], 13, v[50:51]
	v_or_b32_e32 v54, 52, v96
	v_lshl_add_u64 v[50:51], v[98:99], 0, v[50:51]
	v_ashrrev_i32_e32 v55, 31, v54
	global_load_dwordx4 v[50:53], v[50:51], off nt
	v_lshlrev_b64 v[54:55], 13, v[54:55]
	v_or_b32_e32 v58, 56, v96
	v_lshl_add_u64 v[54:55], v[98:99], 0, v[54:55]
	v_ashrrev_i32_e32 v59, 31, v58
	global_load_dwordx4 v[54:57], v[54:55], off nt
	v_lshlrev_b64 v[58:59], 13, v[58:59]
	v_or_b32_e32 v96, 60, v96
	v_lshl_add_u64 v[58:59], v[98:99], 0, v[58:59]
	v_ashrrev_i32_e32 v97, 31, v96
	global_load_dwordx4 v[58:61], v[58:59], off nt
	v_lshlrev_b64 v[96:97], 13, v[96:97]
	v_lshl_add_u64 v[96:97], v[98:99], 0, v[96:97]
	global_load_dwordx4 v[96:99], v[96:97], off nt
	v_add_u32_e32 v1, 0x410, v95
	v_ashrrev_i32_e32 v63, 31, v62
	s_waitcnt vmcnt(15)
	ds_write2_b32 v95, v2, v3 offset1:1
	ds_write2_b32 v95, v4, v5 offset0:2 offset1:3
	s_waitcnt vmcnt(14)
	ds_write2_b32 v1, v6, v7 offset1:1
	v_add_u32_e32 v1, 0x418, v95
	ds_write2_b32 v1, v8, v9 offset1:1
	v_add_u32_e32 v1, 0x820, v95
	v_lshl_add_u64 v[8:9], v[62:63], 1, v[76:77]
	s_waitcnt vmcnt(13)
	ds_write2_b32 v1, v10, v11 offset1:1
	v_add_u32_e32 v1, 0x828, v95
	ds_write2_b32 v1, v12, v13 offset1:1
	v_add_u32_e32 v1, 0xc30, v95
	s_waitcnt vmcnt(12)
	ds_write2_b32 v1, v14, v15 offset1:1
	v_add_u32_e32 v1, 0xc38, v95
	ds_write2_b32 v1, v16, v17 offset1:1
	v_add_u32_e32 v1, 0x1040, v95
	s_waitcnt vmcnt(11)
	ds_write2_b32 v1, v18, v19 offset1:1
	v_add_u32_e32 v1, 0x1048, v95
	ds_write2_b32 v1, v20, v21 offset1:1
	v_add_u32_e32 v1, 0x1450, v95
	s_waitcnt vmcnt(10)
	ds_write2_b32 v1, v22, v23 offset1:1
	v_add_u32_e32 v1, 0x1458, v95
	ds_write2_b32 v1, v24, v25 offset1:1
	v_add_u32_e32 v1, 0x1860, v95
	s_waitcnt vmcnt(9)
	ds_write2_b32 v1, v26, v27 offset1:1
	v_add_u32_e32 v1, 0x1868, v95
	ds_write2_b32 v1, v28, v29 offset1:1
	v_add_u32_e32 v1, 0x1c70, v95
	s_waitcnt vmcnt(8)
	ds_write2_b32 v1, v30, v31 offset1:1
	v_add_u32_e32 v1, 0x1c78, v95
	ds_write2_b32 v1, v32, v33 offset1:1
	v_add_u32_e32 v1, 0x2080, v95
	s_waitcnt vmcnt(7)
	ds_write2_b32 v1, v34, v35 offset1:1
	v_add_u32_e32 v1, 0x2088, v95
	ds_write2_b32 v1, v36, v37 offset1:1
	v_add_u32_e32 v1, 0x2490, v95
	s_waitcnt vmcnt(6)
	ds_write2_b32 v1, v38, v39 offset1:1
	v_add_u32_e32 v1, 0x2498, v95
	ds_write2_b32 v1, v40, v41 offset1:1
	v_add_u32_e32 v1, 0x28a0, v95
	s_waitcnt vmcnt(5)
	ds_write2_b32 v1, v42, v43 offset1:1
	v_add_u32_e32 v1, 0x28a8, v95
	ds_write2_b32 v1, v44, v45 offset1:1
	v_add_u32_e32 v1, 0x2cb0, v95
	s_waitcnt vmcnt(4)
	ds_write2_b32 v1, v46, v47 offset1:1
	v_add_u32_e32 v1, 0x2cb8, v95
	ds_write2_b32 v1, v48, v49 offset1:1
	v_add_u32_e32 v1, 0x30c0, v95
	s_waitcnt vmcnt(3)
	ds_write2_b32 v1, v50, v51 offset1:1
	v_add_u32_e32 v1, 0x30c8, v95
	ds_write2_b32 v1, v52, v53 offset1:1
	v_add_u32_e32 v1, 0x34d0, v95
	s_waitcnt vmcnt(2)
	ds_write2_b32 v1, v54, v55 offset1:1
	v_add_u32_e32 v1, 0x34d8, v95
	ds_write2_b32 v1, v56, v57 offset1:1
	v_add_u32_e32 v1, 0x38e0, v95
	s_waitcnt vmcnt(1)
	ds_write2_b32 v1, v58, v59 offset1:1
	v_add_u32_e32 v1, 0x38e8, v95
	ds_write2_b32 v1, v60, v61 offset1:1
	v_add_u32_e32 v1, 0x3cf0, v95
	s_waitcnt vmcnt(0)
	ds_write2_b32 v1, v96, v97 offset1:1
	v_add_u32_e32 v1, 0x3cf8, v95
	ds_write2_b32 v1, v98, v99 offset1:1
	s_waitcnt lgkmcnt(0)
	ds_read2_b32 v[2:3], v114 offset1:65
	s_waitcnt lgkmcnt(0)
	v_cvt_pk_bf16_f32 v2, v2, v3
	ds_read2_b32 v[4:5], v114 offset0:130 offset1:195
	s_waitcnt lgkmcnt(0)
	v_cvt_pk_bf16_f32 v3, v4, v5
	ds_read2_b32 v[4:5], v124 offset0:4 offset1:69
	s_waitcnt lgkmcnt(0)
	v_cvt_pk_bf16_f32 v4, v4, v5
	ds_read2_b32 v[6:7], v124 offset0:134 offset1:199
	s_waitcnt lgkmcnt(0)
	v_cvt_pk_bf16_f32 v5, v6, v7
	v_or_b32_e32 v6, 0, v254
	v_or_b32_e32 v6, v0, v6
	v_ashrrev_i32_e32 v7, 31, v6
	v_lshlrev_b64 v[6:7], 10, v[6:7]
	v_lshl_add_u64 v[6:7], v[8:9], 0, v[6:7]
	ds_read2_b32 v[10:11], v114 offset0:8 offset1:73
	global_store_dwordx4 v[6:7], v[2:5], off
	s_waitcnt lgkmcnt(0)
	s_nop 0
	v_cvt_pk_bf16_f32 v2, v10, v11
	ds_read2_b32 v[4:5], v114 offset0:138 offset1:203
	s_waitcnt lgkmcnt(0)
	v_cvt_pk_bf16_f32 v3, v4, v5
	ds_read2_b32 v[4:5], v124 offset0:12 offset1:77
	s_waitcnt lgkmcnt(0)
	v_cvt_pk_bf16_f32 v4, v4, v5
	ds_read2_b32 v[6:7], v124 offset0:142 offset1:207
	s_waitcnt lgkmcnt(0)
	v_cvt_pk_bf16_f32 v5, v6, v7
	v_or_b32_e32 v6, 4, v254
	v_or_b32_e32 v6, v0, v6
	v_ashrrev_i32_e32 v7, 31, v6
	v_lshlrev_b64 v[6:7], 10, v[6:7]
	v_lshl_add_u64 v[6:7], v[8:9], 0, v[6:7]
	ds_read2_b32 v[10:11], v114 offset0:16 offset1:81
	global_store_dwordx4 v[6:7], v[2:5], off
	s_waitcnt lgkmcnt(0)
	s_nop 0
	v_cvt_pk_bf16_f32 v2, v10, v11
	ds_read2_b32 v[4:5], v114 offset0:146 offset1:211
	s_waitcnt lgkmcnt(0)
	v_cvt_pk_bf16_f32 v3, v4, v5
	ds_read2_b32 v[4:5], v124 offset0:20 offset1:85
	s_waitcnt lgkmcnt(0)
	v_cvt_pk_bf16_f32 v4, v4, v5
	ds_read2_b32 v[6:7], v124 offset0:150 offset1:215
	s_waitcnt lgkmcnt(0)
	v_cvt_pk_bf16_f32 v5, v6, v7
	v_or_b32_e32 v6, 8, v254
	v_or_b32_e32 v6, v0, v6
	v_ashrrev_i32_e32 v7, 31, v6
	v_lshlrev_b64 v[6:7], 10, v[6:7]
	v_lshl_add_u64 v[6:7], v[8:9], 0, v[6:7]
	ds_read2_b32 v[10:11], v114 offset0:24 offset1:89
	global_store_dwordx4 v[6:7], v[2:5], off
	s_waitcnt lgkmcnt(0)
	s_nop 0
	v_cvt_pk_bf16_f32 v2, v10, v11
	ds_read2_b32 v[4:5], v114 offset0:154 offset1:219
	s_waitcnt lgkmcnt(0)
	v_cvt_pk_bf16_f32 v3, v4, v5
	ds_read2_b32 v[4:5], v124 offset0:28 offset1:93
	s_waitcnt lgkmcnt(0)
	v_cvt_pk_bf16_f32 v4, v4, v5
	ds_read2_b32 v[6:7], v124 offset0:158 offset1:223
	s_waitcnt lgkmcnt(0)
	v_cvt_pk_bf16_f32 v5, v6, v7
	v_or_b32_e32 v6, 12, v254
	v_or_b32_e32 v6, v0, v6
	v_ashrrev_i32_e32 v7, 31, v6
	v_lshlrev_b64 v[6:7], 10, v[6:7]
	v_lshl_add_u64 v[6:7], v[8:9], 0, v[6:7]
	ds_read2_b32 v[10:11], v114 offset0:32 offset1:97
	global_store_dwordx4 v[6:7], v[2:5], off
	s_waitcnt lgkmcnt(0)
	s_nop 0
	v_cvt_pk_bf16_f32 v2, v10, v11
	ds_read2_b32 v[4:5], v114 offset0:162 offset1:227
	s_waitcnt lgkmcnt(0)
	v_cvt_pk_bf16_f32 v3, v4, v5
	ds_read2_b32 v[4:5], v124 offset0:36 offset1:101
	s_waitcnt lgkmcnt(0)
	v_cvt_pk_bf16_f32 v4, v4, v5
	ds_read2_b32 v[6:7], v124 offset0:166 offset1:231
	s_waitcnt lgkmcnt(0)
	v_cvt_pk_bf16_f32 v5, v6, v7
	v_or_b32_e32 v6, 32, v254
	v_or_b32_e32 v6, v0, v6
	v_ashrrev_i32_e32 v7, 31, v6
	v_lshlrev_b64 v[6:7], 10, v[6:7]
	v_lshl_add_u64 v[6:7], v[8:9], 0, v[6:7]
	ds_read2_b32 v[10:11], v114 offset0:40 offset1:105
	global_store_dwordx4 v[6:7], v[2:5], off
	s_waitcnt lgkmcnt(0)
	s_nop 0
	v_cvt_pk_bf16_f32 v2, v10, v11
	ds_read2_b32 v[4:5], v114 offset0:170 offset1:235
	s_waitcnt lgkmcnt(0)
	v_cvt_pk_bf16_f32 v3, v4, v5
	ds_read2_b32 v[4:5], v124 offset0:44 offset1:109
	s_waitcnt lgkmcnt(0)
	v_cvt_pk_bf16_f32 v4, v4, v5
	ds_read2_b32 v[6:7], v124 offset0:174 offset1:239
	s_waitcnt lgkmcnt(0)
	v_cvt_pk_bf16_f32 v5, v6, v7
	v_or_b32_e32 v6, 36, v254
	v_or_b32_e32 v6, v0, v6
	v_ashrrev_i32_e32 v7, 31, v6
	v_lshlrev_b64 v[6:7], 10, v[6:7]
	v_lshl_add_u64 v[6:7], v[8:9], 0, v[6:7]
	ds_read2_b32 v[10:11], v114 offset0:48 offset1:113
	global_store_dwordx4 v[6:7], v[2:5], off
	s_waitcnt lgkmcnt(0)
	s_nop 0
	v_cvt_pk_bf16_f32 v2, v10, v11
	ds_read2_b32 v[4:5], v114 offset0:178 offset1:243
	s_waitcnt lgkmcnt(0)
	v_cvt_pk_bf16_f32 v3, v4, v5
	ds_read2_b32 v[4:5], v124 offset0:52 offset1:117
	s_waitcnt lgkmcnt(0)
	v_cvt_pk_bf16_f32 v4, v4, v5
	ds_read2_b32 v[6:7], v124 offset0:182 offset1:247
	s_waitcnt lgkmcnt(0)
	v_cvt_pk_bf16_f32 v5, v6, v7
	v_or_b32_e32 v6, 40, v254
	v_or_b32_e32 v6, v0, v6
	v_ashrrev_i32_e32 v7, 31, v6
	v_lshlrev_b64 v[6:7], 10, v[6:7]
	v_or_b32_e32 v255, 44, v254
	v_or_b32_e32 v0, v0, v255
	v_lshl_add_u64 v[6:7], v[8:9], 0, v[6:7]
	v_ashrrev_i32_e32 v1, 31, v0
	ds_read2_b32 v[10:11], v114 offset0:56 offset1:121
	global_store_dwordx4 v[6:7], v[2:5], off
	v_lshlrev_b64 v[0:1], 10, v[0:1]
	v_lshl_add_u64 v[0:1], v[8:9], 0, v[0:1]
	s_waitcnt lgkmcnt(0)
	v_cvt_pk_bf16_f32 v2, v10, v11
	ds_read2_b32 v[4:5], v114 offset0:186 offset1:251
	s_waitcnt lgkmcnt(0)
	v_cvt_pk_bf16_f32 v3, v4, v5
	ds_read2_b32 v[4:5], v124 offset0:60 offset1:125
	s_waitcnt lgkmcnt(0)
	v_cvt_pk_bf16_f32 v4, v4, v5
	ds_read2_b32 v[6:7], v124 offset0:190 offset1:255
	s_waitcnt lgkmcnt(0)
	v_cvt_pk_bf16_f32 v5, v6, v7
	global_store_dwordx4 v[0:1], v[2:5], off
	s_waitcnt lgkmcnt(0)
	s_or_b64 exec, exec, s[0:1]
	s_and_b64 exec, exec, vcc
	s_cbranch_execz .LBB0_24

.LBB0_1334:
	v_lshl_add_u32 v164, s26, 8, v144
	v_and_b32_e32 v151, 12, v146
	v_add_u32_e32 v151, v146, v151
	v_lshl_or_b32 v140, s28, 8, v151
	v_ashrrev_i32_e32 v165, 31, v164
	v_ashrrev_i32_e32 v141, 31, v140
	v_lshlrev_b64 v[152:153], 11, v[164:165]
	v_lshl_add_u64 v[152:153], v[152:153], 0, v[140:141]
	v_lshlrev_b64 v[152:153], 1, v[152:153]
	v_lshl_add_u64 v[160:161], s[6:7], 0, v[152:153]
	v_lshl_add_u64 v[162:163], s[8:9], 0, v[152:153]
	global_load_dwordx4 v[168:171], v[160:161], off
	global_load_dwordx4 v[172:175], v[160:161], off offset:256
	v_mov_b64_e32 v[154:155], v[160:161]
	v_mov_b64_e32 v[156:157], v[162:163]
	v_xor_b32_e32 v194, 16, v150
	v_lshlrev_b32_e32 v194, 2, v194
	v_xor_b32_e32 v195, 32, v150
	v_lshlrev_b32_e32 v195, 2, v195
	s_mov_b32 s90, 0x10000
	s_mov_b32 s91, 0
	s_mov_b32 s92, 0x80000
	s_mov_b32 s93, 0
	v_lshl_add_u64 v[160:161], v[160:161], 0, s[90:91]
	global_load_dwordx4 v[200:203], v[160:161], off
	global_load_dwordx4 v[204:207], v[160:161], off offset:256
	s_waitcnt vmcnt(2)
	v_lshlrev_b32_e32 v176, 16, v168
	v_and_b32_e32 v177, 0xffff0000, v168
	v_lshlrev_b32_e32 v178, 16, v169
	v_and_b32_e32 v179, 0xffff0000, v169
	v_pk_add_f32 v[124:125], v[124:125], v[176:177]
	v_pk_add_f32 v[126:127], v[126:127], v[178:179]
	v_cvt_pk_bf16_f32 v184, v124, v125
	v_cvt_pk_bf16_f32 v185, v126, v127
	v_mul_f32_e32 v192, v124, v124
	v_fmac_f32_e32 v192, v125, v125
	v_fmac_f32_e32 v192, v126, v126
	v_fmac_f32_e32 v192, v127, v127
	v_lshlrev_b32_e32 v176, 16, v170
	v_and_b32_e32 v177, 0xffff0000, v170
	v_lshlrev_b32_e32 v178, 16, v171
	v_and_b32_e32 v179, 0xffff0000, v171
	v_pk_add_f32 v[120:121], v[120:121], v[176:177]
	v_pk_add_f32 v[122:123], v[122:123], v[178:179]
	v_cvt_pk_bf16_f32 v186, v120, v121
	v_cvt_pk_bf16_f32 v187, v122, v123
	v_fmac_f32_e32 v192, v120, v120
	v_fmac_f32_e32 v192, v121, v121
	v_fmac_f32_e32 v192, v122, v122
	v_fmac_f32_e32 v192, v123, v123
	global_store_dwordx4 v[162:163], v[184:187], off
	v_lshlrev_b32_e32 v176, 16, v172
	v_and_b32_e32 v177, 0xffff0000, v172
	v_lshlrev_b32_e32 v178, 16, v173
	v_and_b32_e32 v179, 0xffff0000, v173
	v_pk_add_f32 v[116:117], v[116:117], v[176:177]
	v_pk_add_f32 v[118:119], v[118:119], v[178:179]
	v_cvt_pk_bf16_f32 v188, v116, v117
	v_cvt_pk_bf16_f32 v189, v118, v119
	v_fmac_f32_e32 v192, v116, v116
	v_fmac_f32_e32 v192, v117, v117
	v_fmac_f32_e32 v192, v118, v118
	v_fmac_f32_e32 v192, v119, v119
	v_lshlrev_b32_e32 v176, 16, v174
	v_and_b32_e32 v177, 0xffff0000, v174
	v_lshlrev_b32_e32 v178, 16, v175
	v_and_b32_e32 v179, 0xffff0000, v175
	v_pk_add_f32 v[112:113], v[112:113], v[176:177]
	v_pk_add_f32 v[114:115], v[114:115], v[178:179]
	v_cvt_pk_bf16_f32 v190, v112, v113
	v_cvt_pk_bf16_f32 v191, v114, v115
	v_fmac_f32_e32 v192, v112, v112
	v_fmac_f32_e32 v192, v113, v113
	v_fmac_f32_e32 v192, v114, v114
	v_fmac_f32_e32 v192, v115, v115
	global_store_dwordx4 v[162:163], v[188:191], off offset:256
	ds_bpermute_b32 v193, v194, v192
	s_waitcnt lgkmcnt(0)
	v_add_f32_e32 v192, v192, v193
	ds_bpermute_b32 v193, v195, v192
	v_lshl_add_u64 v[196:197], v[164:165], 2, s[10:11]
	s_waitcnt lgkmcnt(0)
	v_add_f32_e32 v192, v192, v193
	s_and_saveexec_b64 s[26:27], s[0:1]
	global_atomic_add_f32 v[196:197], v192, off
	s_or_b64 exec, exec, s[26:27]
	v_lshl_add_u64 v[162:163], v[162:163], 0, s[90:91]
	v_add_u32_e32 v164, 16, v164
	v_lshl_add_u64 v[160:161], v[160:161], 0, s[90:91]
	global_load_dwordx4 v[168:171], v[160:161], off
	global_load_dwordx4 v[172:175], v[160:161], off offset:256
	s_waitcnt vmcnt(4)
	v_lshlrev_b32_e32 v176, 16, v200
	v_and_b32_e32 v177, 0xffff0000, v200
	v_lshlrev_b32_e32 v178, 16, v201
	v_and_b32_e32 v179, 0xffff0000, v201
	v_pk_add_f32 v[108:109], v[108:109], v[176:177]
	v_pk_add_f32 v[110:111], v[110:111], v[178:179]
	v_cvt_pk_bf16_f32 v184, v108, v109
	v_cvt_pk_bf16_f32 v185, v110, v111
	v_mul_f32_e32 v192, v108, v108
	v_fmac_f32_e32 v192, v109, v109
	v_fmac_f32_e32 v192, v110, v110
	v_fmac_f32_e32 v192, v111, v111
	v_lshlrev_b32_e32 v176, 16, v202
	v_and_b32_e32 v177, 0xffff0000, v202
	v_lshlrev_b32_e32 v178, 16, v203
	v_and_b32_e32 v179, 0xffff0000, v203
	v_pk_add_f32 v[104:105], v[104:105], v[176:177]
	v_pk_add_f32 v[106:107], v[106:107], v[178:179]
	v_cvt_pk_bf16_f32 v186, v104, v105
	v_cvt_pk_bf16_f32 v187, v106, v107
	v_fmac_f32_e32 v192, v104, v104
	v_fmac_f32_e32 v192, v105, v105
	v_fmac_f32_e32 v192, v106, v106
	v_fmac_f32_e32 v192, v107, v107
	global_store_dwordx4 v[162:163], v[184:187], off
	v_lshlrev_b32_e32 v176, 16, v204
	v_and_b32_e32 v177, 0xffff0000, v204
	v_lshlrev_b32_e32 v178, 16, v205
	v_and_b32_e32 v179, 0xffff0000, v205
	v_pk_add_f32 v[100:101], v[100:101], v[176:177]
	v_pk_add_f32 v[102:103], v[102:103], v[178:179]
	v_cvt_pk_bf16_f32 v188, v100, v101
	v_cvt_pk_bf16_f32 v189, v102, v103
	v_fmac_f32_e32 v192, v100, v100
	v_fmac_f32_e32 v192, v101, v101
	v_fmac_f32_e32 v192, v102, v102
	v_fmac_f32_e32 v192, v103, v103
	v_lshlrev_b32_e32 v176, 16, v206
	v_and_b32_e32 v177, 0xffff0000, v206
	v_lshlrev_b32_e32 v178, 16, v207
	v_and_b32_e32 v179, 0xffff0000, v207
	v_pk_add_f32 v[96:97], v[96:97], v[176:177]
	v_pk_add_f32 v[98:99], v[98:99], v[178:179]
	v_cvt_pk_bf16_f32 v190, v96, v97
	v_cvt_pk_bf16_f32 v191, v98, v99
	v_fmac_f32_e32 v192, v96, v96
	v_fmac_f32_e32 v192, v97, v97
	v_fmac_f32_e32 v192, v98, v98
	v_fmac_f32_e32 v192, v99, v99
	global_store_dwordx4 v[162:163], v[188:191], off offset:256
	ds_bpermute_b32 v193, v194, v192
	s_waitcnt lgkmcnt(0)
	v_add_f32_e32 v192, v192, v193
	ds_bpermute_b32 v193, v195, v192
	v_lshl_add_u64 v[196:197], v[164:165], 2, s[10:11]
	s_waitcnt lgkmcnt(0)
	v_add_f32_e32 v192, v192, v193
	s_and_saveexec_b64 s[26:27], s[0:1]
	global_atomic_add_f32 v[196:197], v192, off
	s_or_b64 exec, exec, s[26:27]
	v_lshl_add_u64 v[162:163], v[162:163], 0, s[90:91]
	v_add_u32_e32 v164, 16, v164
	v_lshl_add_u64 v[160:161], v[160:161], 0, s[90:91]
	global_load_dwordx4 v[200:203], v[160:161], off
	global_load_dwordx4 v[204:207], v[160:161], off offset:256
	s_waitcnt vmcnt(4)
	v_lshlrev_b32_e32 v176, 16, v168
	v_and_b32_e32 v177, 0xffff0000, v168
	v_lshlrev_b32_e32 v178, 16, v169
	v_and_b32_e32 v179, 0xffff0000, v169
	v_pk_add_f32 v[92:93], v[92:93], v[176:177]
	v_pk_add_f32 v[94:95], v[94:95], v[178:179]
	v_cvt_pk_bf16_f32 v184, v92, v93
	v_cvt_pk_bf16_f32 v185, v94, v95
	v_mul_f32_e32 v192, v92, v92
	v_fmac_f32_e32 v192, v93, v93
	v_fmac_f32_e32 v192, v94, v94
	v_fmac_f32_e32 v192, v95, v95
	v_lshlrev_b32_e32 v176, 16, v170
	v_and_b32_e32 v177, 0xffff0000, v170
	v_lshlrev_b32_e32 v178, 16, v171
	v_and_b32_e32 v179, 0xffff0000, v171
	v_pk_add_f32 v[88:89], v[88:89], v[176:177]
	v_pk_add_f32 v[90:91], v[90:91], v[178:179]
	v_cvt_pk_bf16_f32 v186, v88, v89
	v_cvt_pk_bf16_f32 v187, v90, v91
	v_fmac_f32_e32 v192, v88, v88
	v_fmac_f32_e32 v192, v89, v89
	v_fmac_f32_e32 v192, v90, v90
	v_fmac_f32_e32 v192, v91, v91
	global_store_dwordx4 v[162:163], v[184:187], off
	v_lshlrev_b32_e32 v176, 16, v172
	v_and_b32_e32 v177, 0xffff0000, v172
	v_lshlrev_b32_e32 v178, 16, v173
	v_and_b32_e32 v179, 0xffff0000, v173
	v_pk_add_f32 v[84:85], v[84:85], v[176:177]
	v_pk_add_f32 v[86:87], v[86:87], v[178:179]
	v_cvt_pk_bf16_f32 v188, v84, v85
	v_cvt_pk_bf16_f32 v189, v86, v87
	v_fmac_f32_e32 v192, v84, v84
	v_fmac_f32_e32 v192, v85, v85
	v_fmac_f32_e32 v192, v86, v86
	v_fmac_f32_e32 v192, v87, v87
	v_lshlrev_b32_e32 v176, 16, v174
	v_and_b32_e32 v177, 0xffff0000, v174
	v_lshlrev_b32_e32 v178, 16, v175
	v_and_b32_e32 v179, 0xffff0000, v175
	v_pk_add_f32 v[80:81], v[80:81], v[176:177]
	v_pk_add_f32 v[82:83], v[82:83], v[178:179]
	v_cvt_pk_bf16_f32 v190, v80, v81
	v_cvt_pk_bf16_f32 v191, v82, v83
	v_fmac_f32_e32 v192, v80, v80
	v_fmac_f32_e32 v192, v81, v81
	v_fmac_f32_e32 v192, v82, v82
	v_fmac_f32_e32 v192, v83, v83
	global_store_dwordx4 v[162:163], v[188:191], off offset:256
	ds_bpermute_b32 v193, v194, v192
	s_waitcnt lgkmcnt(0)
	v_add_f32_e32 v192, v192, v193
	ds_bpermute_b32 v193, v195, v192
	v_lshl_add_u64 v[196:197], v[164:165], 2, s[10:11]
	s_waitcnt lgkmcnt(0)
	v_add_f32_e32 v192, v192, v193
	s_and_saveexec_b64 s[26:27], s[0:1]
	global_atomic_add_f32 v[196:197], v192, off
	s_or_b64 exec, exec, s[26:27]
	v_lshl_add_u64 v[162:163], v[162:163], 0, s[90:91]
	v_add_u32_e32 v164, 16, v164
	v_lshl_add_u64 v[160:161], v[154:155], 0, s[92:93]
	global_load_dwordx4 v[168:171], v[160:161], off
	global_load_dwordx4 v[172:175], v[160:161], off offset:256
	s_waitcnt vmcnt(4)
	v_lshlrev_b32_e32 v176, 16, v200
	v_and_b32_e32 v177, 0xffff0000, v200
	v_lshlrev_b32_e32 v178, 16, v201
	v_and_b32_e32 v179, 0xffff0000, v201
	v_pk_add_f32 v[76:77], v[76:77], v[176:177]
	v_pk_add_f32 v[78:79], v[78:79], v[178:179]
	v_cvt_pk_bf16_f32 v184, v76, v77
	v_cvt_pk_bf16_f32 v185, v78, v79
	v_mul_f32_e32 v192, v76, v76
	v_fmac_f32_e32 v192, v77, v77
	v_fmac_f32_e32 v192, v78, v78
	v_fmac_f32_e32 v192, v79, v79
	v_lshlrev_b32_e32 v176, 16, v202
	v_and_b32_e32 v177, 0xffff0000, v202
	v_lshlrev_b32_e32 v178, 16, v203
	v_and_b32_e32 v179, 0xffff0000, v203
	v_pk_add_f32 v[72:73], v[72:73], v[176:177]
	v_pk_add_f32 v[74:75], v[74:75], v[178:179]
	v_cvt_pk_bf16_f32 v186, v72, v73
	v_cvt_pk_bf16_f32 v187, v74, v75
	v_fmac_f32_e32 v192, v72, v72
	v_fmac_f32_e32 v192, v73, v73
	v_fmac_f32_e32 v192, v74, v74
	v_fmac_f32_e32 v192, v75, v75
	global_store_dwordx4 v[162:163], v[184:187], off
	v_lshlrev_b32_e32 v176, 16, v204
	v_and_b32_e32 v177, 0xffff0000, v204
	v_lshlrev_b32_e32 v178, 16, v205
	v_and_b32_e32 v179, 0xffff0000, v205
	v_pk_add_f32 v[68:69], v[68:69], v[176:177]
	v_pk_add_f32 v[70:71], v[70:71], v[178:179]
	v_cvt_pk_bf16_f32 v188, v68, v69
	v_cvt_pk_bf16_f32 v189, v70, v71
	v_fmac_f32_e32 v192, v68, v68
	v_fmac_f32_e32 v192, v69, v69
	v_fmac_f32_e32 v192, v70, v70
	v_fmac_f32_e32 v192, v71, v71
	v_lshlrev_b32_e32 v176, 16, v206
	v_and_b32_e32 v177, 0xffff0000, v206
	v_lshlrev_b32_e32 v178, 16, v207
	v_and_b32_e32 v179, 0xffff0000, v207
	v_pk_add_f32 v[64:65], v[64:65], v[176:177]
	v_pk_add_f32 v[66:67], v[66:67], v[178:179]
	v_cvt_pk_bf16_f32 v190, v64, v65
	v_cvt_pk_bf16_f32 v191, v66, v67
	v_fmac_f32_e32 v192, v64, v64
	v_fmac_f32_e32 v192, v65, v65
	v_fmac_f32_e32 v192, v66, v66
	v_fmac_f32_e32 v192, v67, v67
	global_store_dwordx4 v[162:163], v[188:191], off offset:256
	ds_bpermute_b32 v193, v194, v192
	s_waitcnt lgkmcnt(0)
	v_add_f32_e32 v192, v192, v193
	ds_bpermute_b32 v193, v195, v192
	v_lshl_add_u64 v[196:197], v[164:165], 2, s[10:11]
	s_waitcnt lgkmcnt(0)
	v_add_f32_e32 v192, v192, v193
	s_and_saveexec_b64 s[26:27], s[0:1]
	global_atomic_add_f32 v[196:197], v192, off
	s_or_b64 exec, exec, s[26:27]
	v_lshl_add_u64 v[162:163], v[156:157], 0, s[92:93]
	v_add_u32_e32 v164, 0x50, v164
	v_lshl_add_u64 v[160:161], v[160:161], 0, s[90:91]
	global_load_dwordx4 v[200:203], v[160:161], off
	global_load_dwordx4 v[204:207], v[160:161], off offset:256
	s_waitcnt vmcnt(4)
	v_lshlrev_b32_e32 v176, 16, v168
	v_and_b32_e32 v177, 0xffff0000, v168
	v_lshlrev_b32_e32 v178, 16, v169
	v_and_b32_e32 v179, 0xffff0000, v169
	v_pk_add_f32 v[60:61], v[60:61], v[176:177]
	v_pk_add_f32 v[62:63], v[62:63], v[178:179]
	v_cvt_pk_bf16_f32 v184, v60, v61
	v_cvt_pk_bf16_f32 v185, v62, v63
	v_mul_f32_e32 v192, v60, v60
	v_fmac_f32_e32 v192, v61, v61
	v_fmac_f32_e32 v192, v62, v62
	v_fmac_f32_e32 v192, v63, v63
	v_lshlrev_b32_e32 v176, 16, v170
	v_and_b32_e32 v177, 0xffff0000, v170
	v_lshlrev_b32_e32 v178, 16, v171
	v_and_b32_e32 v179, 0xffff0000, v171
	v_pk_add_f32 v[56:57], v[56:57], v[176:177]
	v_pk_add_f32 v[58:59], v[58:59], v[178:179]
	v_cvt_pk_bf16_f32 v186, v56, v57
	v_cvt_pk_bf16_f32 v187, v58, v59
	v_fmac_f32_e32 v192, v56, v56
	v_fmac_f32_e32 v192, v57, v57
	v_fmac_f32_e32 v192, v58, v58
	v_fmac_f32_e32 v192, v59, v59
	global_store_dwordx4 v[162:163], v[184:187], off
	v_lshlrev_b32_e32 v176, 16, v172
	v_and_b32_e32 v177, 0xffff0000, v172
	v_lshlrev_b32_e32 v178, 16, v173
	v_and_b32_e32 v179, 0xffff0000, v173
	v_pk_add_f32 v[52:53], v[52:53], v[176:177]
	v_pk_add_f32 v[54:55], v[54:55], v[178:179]
	v_cvt_pk_bf16_f32 v188, v52, v53
	v_cvt_pk_bf16_f32 v189, v54, v55
	v_fmac_f32_e32 v192, v52, v52
	v_fmac_f32_e32 v192, v53, v53
	v_fmac_f32_e32 v192, v54, v54
	v_fmac_f32_e32 v192, v55, v55
	v_lshlrev_b32_e32 v176, 16, v174
	v_and_b32_e32 v177, 0xffff0000, v174
	v_lshlrev_b32_e32 v178, 16, v175
	v_and_b32_e32 v179, 0xffff0000, v175
	v_pk_add_f32 v[48:49], v[48:49], v[176:177]
	v_pk_add_f32 v[50:51], v[50:51], v[178:179]
	v_cvt_pk_bf16_f32 v190, v48, v49
	v_cvt_pk_bf16_f32 v191, v50, v51
	v_fmac_f32_e32 v192, v48, v48
	v_fmac_f32_e32 v192, v49, v49
	v_fmac_f32_e32 v192, v50, v50
	v_fmac_f32_e32 v192, v51, v51
	global_store_dwordx4 v[162:163], v[188:191], off offset:256
	ds_bpermute_b32 v193, v194, v192
	s_waitcnt lgkmcnt(0)
	v_add_f32_e32 v192, v192, v193
	ds_bpermute_b32 v193, v195, v192
	v_lshl_add_u64 v[196:197], v[164:165], 2, s[10:11]
	s_waitcnt lgkmcnt(0)
	v_add_f32_e32 v192, v192, v193
	s_and_saveexec_b64 s[26:27], s[0:1]
	global_atomic_add_f32 v[196:197], v192, off
	s_or_b64 exec, exec, s[26:27]
	v_lshl_add_u64 v[162:163], v[162:163], 0, s[90:91]
	v_add_u32_e32 v164, 16, v164
	v_lshl_add_u64 v[160:161], v[160:161], 0, s[90:91]
	global_load_dwordx4 v[168:171], v[160:161], off
	global_load_dwordx4 v[172:175], v[160:161], off offset:256
	s_waitcnt vmcnt(4)
	v_lshlrev_b32_e32 v176, 16, v200
	v_and_b32_e32 v177, 0xffff0000, v200
	v_lshlrev_b32_e32 v178, 16, v201
	v_and_b32_e32 v179, 0xffff0000, v201
	v_pk_add_f32 v[44:45], v[44:45], v[176:177]
	v_pk_add_f32 v[46:47], v[46:47], v[178:179]
	v_cvt_pk_bf16_f32 v184, v44, v45
	v_cvt_pk_bf16_f32 v185, v46, v47
	v_mul_f32_e32 v192, v44, v44
	v_fmac_f32_e32 v192, v45, v45
	v_fmac_f32_e32 v192, v46, v46
	v_fmac_f32_e32 v192, v47, v47
	v_lshlrev_b32_e32 v176, 16, v202
	v_and_b32_e32 v177, 0xffff0000, v202
	v_lshlrev_b32_e32 v178, 16, v203
	v_and_b32_e32 v179, 0xffff0000, v203
	v_pk_add_f32 v[40:41], v[40:41], v[176:177]
	v_pk_add_f32 v[42:43], v[42:43], v[178:179]
	v_cvt_pk_bf16_f32 v186, v40, v41
	v_cvt_pk_bf16_f32 v187, v42, v43
	v_fmac_f32_e32 v192, v40, v40
	v_fmac_f32_e32 v192, v41, v41
	v_fmac_f32_e32 v192, v42, v42
	v_fmac_f32_e32 v192, v43, v43
	global_store_dwordx4 v[162:163], v[184:187], off
	v_lshlrev_b32_e32 v176, 16, v204
	v_and_b32_e32 v177, 0xffff0000, v204
	v_lshlrev_b32_e32 v178, 16, v205
	v_and_b32_e32 v179, 0xffff0000, v205
	v_pk_add_f32 v[36:37], v[36:37], v[176:177]
	v_pk_add_f32 v[38:39], v[38:39], v[178:179]
	v_cvt_pk_bf16_f32 v188, v36, v37
	v_cvt_pk_bf16_f32 v189, v38, v39
	v_fmac_f32_e32 v192, v36, v36
	v_fmac_f32_e32 v192, v37, v37
	v_fmac_f32_e32 v192, v38, v38
	v_fmac_f32_e32 v192, v39, v39
	v_lshlrev_b32_e32 v176, 16, v206
	v_and_b32_e32 v177, 0xffff0000, v206
	v_lshlrev_b32_e32 v178, 16, v207
	v_and_b32_e32 v179, 0xffff0000, v207
	v_pk_add_f32 v[32:33], v[32:33], v[176:177]
	v_pk_add_f32 v[34:35], v[34:35], v[178:179]
	v_cvt_pk_bf16_f32 v190, v32, v33
	v_cvt_pk_bf16_f32 v191, v34, v35
	v_fmac_f32_e32 v192, v32, v32
	v_fmac_f32_e32 v192, v33, v33
	v_fmac_f32_e32 v192, v34, v34
	v_fmac_f32_e32 v192, v35, v35
	global_store_dwordx4 v[162:163], v[188:191], off offset:256
	ds_bpermute_b32 v193, v194, v192
	s_waitcnt lgkmcnt(0)
	v_add_f32_e32 v192, v192, v193
	ds_bpermute_b32 v193, v195, v192
	v_lshl_add_u64 v[196:197], v[164:165], 2, s[10:11]
	s_waitcnt lgkmcnt(0)
	v_add_f32_e32 v192, v192, v193
	s_and_saveexec_b64 s[26:27], s[0:1]
	global_atomic_add_f32 v[196:197], v192, off
	s_or_b64 exec, exec, s[26:27]
	v_lshl_add_u64 v[162:163], v[162:163], 0, s[90:91]
	v_add_u32_e32 v164, 16, v164
	v_lshl_add_u64 v[160:161], v[160:161], 0, s[90:91]
	global_load_dwordx4 v[200:203], v[160:161], off
	global_load_dwordx4 v[204:207], v[160:161], off offset:256
	s_waitcnt vmcnt(4)
	v_lshlrev_b32_e32 v176, 16, v168
	v_and_b32_e32 v177, 0xffff0000, v168
	v_lshlrev_b32_e32 v178, 16, v169
	v_and_b32_e32 v179, 0xffff0000, v169
	v_pk_add_f32 v[28:29], v[28:29], v[176:177]
	v_pk_add_f32 v[30:31], v[30:31], v[178:179]
	v_cvt_pk_bf16_f32 v184, v28, v29
	v_cvt_pk_bf16_f32 v185, v30, v31
	v_mul_f32_e32 v192, v28, v28
	v_fmac_f32_e32 v192, v29, v29
	v_fmac_f32_e32 v192, v30, v30
	v_fmac_f32_e32 v192, v31, v31
	v_lshlrev_b32_e32 v176, 16, v170
	v_and_b32_e32 v177, 0xffff0000, v170
	v_lshlrev_b32_e32 v178, 16, v171
	v_and_b32_e32 v179, 0xffff0000, v171
	v_pk_add_f32 v[24:25], v[24:25], v[176:177]
	v_pk_add_f32 v[26:27], v[26:27], v[178:179]
	v_cvt_pk_bf16_f32 v186, v24, v25
	v_cvt_pk_bf16_f32 v187, v26, v27
	v_fmac_f32_e32 v192, v24, v24
	v_fmac_f32_e32 v192, v25, v25
	v_fmac_f32_e32 v192, v26, v26
	v_fmac_f32_e32 v192, v27, v27
	global_store_dwordx4 v[162:163], v[184:187], off
	v_lshlrev_b32_e32 v176, 16, v172
	v_and_b32_e32 v177, 0xffff0000, v172
	v_lshlrev_b32_e32 v178, 16, v173
	v_and_b32_e32 v179, 0xffff0000, v173
	v_pk_add_f32 v[20:21], v[20:21], v[176:177]
	v_pk_add_f32 v[22:23], v[22:23], v[178:179]
	v_cvt_pk_bf16_f32 v188, v20, v21
	v_cvt_pk_bf16_f32 v189, v22, v23
	v_fmac_f32_e32 v192, v20, v20
	v_fmac_f32_e32 v192, v21, v21
	v_fmac_f32_e32 v192, v22, v22
	v_fmac_f32_e32 v192, v23, v23
	v_lshlrev_b32_e32 v176, 16, v174
	v_and_b32_e32 v177, 0xffff0000, v174
	v_lshlrev_b32_e32 v178, 16, v175
	v_and_b32_e32 v179, 0xffff0000, v175
	v_pk_add_f32 v[16:17], v[16:17], v[176:177]
	v_pk_add_f32 v[18:19], v[18:19], v[178:179]
	v_cvt_pk_bf16_f32 v190, v16, v17
	v_cvt_pk_bf16_f32 v191, v18, v19
	v_fmac_f32_e32 v192, v16, v16
	v_fmac_f32_e32 v192, v17, v17
	v_fmac_f32_e32 v192, v18, v18
	v_fmac_f32_e32 v192, v19, v19
	global_store_dwordx4 v[162:163], v[188:191], off offset:256
	ds_bpermute_b32 v193, v194, v192
	s_waitcnt lgkmcnt(0)
	v_add_f32_e32 v192, v192, v193
	ds_bpermute_b32 v193, v195, v192
	v_lshl_add_u64 v[196:197], v[164:165], 2, s[10:11]
	s_waitcnt lgkmcnt(0)
	v_add_f32_e32 v192, v192, v193
	s_and_saveexec_b64 s[26:27], s[0:1]
	global_atomic_add_f32 v[196:197], v192, off
	s_or_b64 exec, exec, s[26:27]
	v_lshl_add_u64 v[162:163], v[162:163], 0, s[90:91]
	v_add_u32_e32 v164, 16, v164
	s_waitcnt vmcnt(2)
	v_lshlrev_b32_e32 v176, 16, v200
	v_and_b32_e32 v177, 0xffff0000, v200
	v_lshlrev_b32_e32 v178, 16, v201
	v_and_b32_e32 v179, 0xffff0000, v201
	v_pk_add_f32 v[12:13], v[12:13], v[176:177]
	v_pk_add_f32 v[14:15], v[14:15], v[178:179]
	v_cvt_pk_bf16_f32 v184, v12, v13
	v_cvt_pk_bf16_f32 v185, v14, v15
	v_mul_f32_e32 v192, v12, v12
	v_fmac_f32_e32 v192, v13, v13
	v_fmac_f32_e32 v192, v14, v14
	v_fmac_f32_e32 v192, v15, v15
	v_lshlrev_b32_e32 v176, 16, v202
	v_and_b32_e32 v177, 0xffff0000, v202
	v_lshlrev_b32_e32 v178, 16, v203
	v_and_b32_e32 v179, 0xffff0000, v203
	v_pk_add_f32 v[8:9], v[8:9], v[176:177]
	v_pk_add_f32 v[10:11], v[10:11], v[178:179]
	v_cvt_pk_bf16_f32 v186, v8, v9
	v_cvt_pk_bf16_f32 v187, v10, v11
	v_fmac_f32_e32 v192, v8, v8
	v_fmac_f32_e32 v192, v9, v9
	v_fmac_f32_e32 v192, v10, v10
	v_fmac_f32_e32 v192, v11, v11
	global_store_dwordx4 v[162:163], v[184:187], off
	v_lshlrev_b32_e32 v176, 16, v204
	v_and_b32_e32 v177, 0xffff0000, v204
	v_lshlrev_b32_e32 v178, 16, v205
	v_and_b32_e32 v179, 0xffff0000, v205
	v_pk_add_f32 v[4:5], v[4:5], v[176:177]
	v_pk_add_f32 v[6:7], v[6:7], v[178:179]
	v_cvt_pk_bf16_f32 v188, v4, v5
	v_cvt_pk_bf16_f32 v189, v6, v7
	v_fmac_f32_e32 v192, v4, v4
	v_fmac_f32_e32 v192, v5, v5
	v_fmac_f32_e32 v192, v6, v6
	v_fmac_f32_e32 v192, v7, v7
	v_lshlrev_b32_e32 v176, 16, v206
	v_and_b32_e32 v177, 0xffff0000, v206
	v_lshlrev_b32_e32 v178, 16, v207
	v_and_b32_e32 v179, 0xffff0000, v207
	v_pk_add_f32 v[0:1], v[0:1], v[176:177]
	v_pk_add_f32 v[2:3], v[2:3], v[178:179]
	v_cvt_pk_bf16_f32 v190, v0, v1
	v_cvt_pk_bf16_f32 v191, v2, v3
	v_fmac_f32_e32 v192, v0, v0
	v_fmac_f32_e32 v192, v1, v1
	v_fmac_f32_e32 v192, v2, v2
	v_fmac_f32_e32 v192, v3, v3
	global_store_dwordx4 v[162:163], v[188:191], off offset:256
	ds_bpermute_b32 v193, v194, v192
	s_waitcnt lgkmcnt(0)
	v_add_f32_e32 v192, v192, v193
	ds_bpermute_b32 v193, v195, v192
	v_lshl_add_u64 v[196:197], v[164:165], 2, s[10:11]
	s_waitcnt lgkmcnt(0)
	v_add_f32_e32 v192, v192, v193
	s_and_saveexec_b64 s[26:27], s[0:1]
	global_atomic_add_f32 v[196:197], v192, off
	s_or_b64 exec, exec, s[26:27]
	s_andn2_b64 vcc, exec, s[2:3]
	s_mov_b64 s[2:3], -1
	s_cbranch_vccnz .LBB0_1323
	s_andn2_b64 vcc, exec, s[4:5]
	s_cbranch_vccnz .LBB0_1322
	s_barrier
	s_branch .LBB0_1322
